# v23 + GEMM k-loops: per-phase s_setprio flips deleted, no static raise (A/B of the priority lever)
# speedup vs baseline: 1.0007x; 1.0007x over previous
.LBB0_210:
	s_or_b64 exec, exec, s[4:5]
	s_and_b64 vcc, exec, s[44:45]
	s_cbranch_vccnz .LBB0_229
.LBB0_211:
	s_add_i32 s60, s60, 1
	s_mov_b64 s[36:37], s[18:19]
	s_mul_i32 s18, s60, s26
	s_add_i32 s38, s18, s2
	s_cmpk_gt_i32 s38, 0x1ff
	s_cselect_b64 s[44:45], -1, 0
	s_lshl_b32 s18, s38, 3
	s_and_b32 s18, s18, 56
	s_bfe_u32 s19, s38, 0x30003
	s_mov_b32 s27, s61
	s_or_b32 s61, s18, s19
	s_mov_b32 s3, s42
	s_ashr_i32 s42, s38, 6
	s_lshl_b32 s18, s61, 19
	s_mov_b64 s[4:5], s[20:21]
	s_add_u32 s20, s14, s18
	s_addc_u32 s21, s15, 0
	s_ashr_i32 s43, s42, 31
	s_lshl_b64 s[18:19], s[42:43], 19
	s_add_u32 s18, s16, s18
	s_addc_u32 s19, s17, s19
	s_cmpk_lt_i32 s38, 0x200
	s_cselect_b32 s38, s21, s5
	s_cselect_b32 s43, s20, s4
	s_cselect_b32 s62, s19, s37
	s_cselect_b32 s63, s18, s36
	s_add_u32 s64, s36, 0x100
	s_addc_u32 s65, s37, 0
	s_mov_b32 s66, -2
	s_waitcnt lgkmcnt(0)
	s_add_u32 s36, s4, 0x100
	s_addc_u32 s37, s5, 0
	s_add_i32 s67, 0, 0x10000
	v_add_u32_e32 v1, s67, v191
	ds_read_b128 v[34:37], v1
	ds_read_b128 v[38:41], v1 offset:1024
	ds_read_b128 v[42:45], v1 offset:2048
	ds_read_b128 v[46:49], v1 offset:3072
	s_cmp_eq_u32 s66, 12
	s_cselect_b32 s49, s38, s37
	s_cselect_b32 s48, s43, s36
	s_cselect_b32 s47, s62, s65
	s_cselect_b32 s46, s63, s64
	v_lshl_add_u64 v[186:187], s[4:5], 0, v[168:169]
	s_add_i32 m0, s53, 0xc000
	ds_read_b128 v[50:53], v206
	ds_read_b128 v[58:61], v206 offset:1024
	ds_read_b128 v[62:65], v206 offset:2048
	ds_read_b128 v[66:69], v206 offset:3072
	ds_read_b128 v[170:173], v206 offset:4096
	ds_read_b128 v[174:177], v206 offset:5120
	ds_read_b128 v[178:181], v206 offset:6144
	ds_read_b128 v[182:185], v206 offset:7168
	global_load_lds_dwordx4 v[186:187], off
	v_lshl_add_u64 v[186:187], s[4:5], 0, v[166:167]
	s_add_i32 m0, s53, 0xe000
	s_nop 0
	global_load_lds_dwordx4 v[186:187], off
	s_waitcnt lgkmcnt(8)
	s_barrier
	s_waitcnt lgkmcnt(0)
	s_waitcnt lgkmcnt(0)
	v_mfma_f32_16x16x32_bf16 v[158:161], v[34:37], v[50:53], 0
	v_mfma_f32_16x16x32_bf16 v[154:157], v[42:45], v[50:53], 0
	v_mfma_f32_16x16x32_bf16 v[142:145], v[34:37], v[62:65], 0
	v_mfma_f32_16x16x32_bf16 v[138:141], v[42:45], v[62:65], 0
	v_mfma_f32_16x16x32_bf16 v[126:129], v[34:37], v[170:173], 0
	v_mfma_f32_16x16x32_bf16 v[122:125], v[42:45], v[170:173], 0
	v_mfma_f32_16x16x32_bf16 v[110:113], v[34:37], v[178:181], 0
	v_mfma_f32_16x16x32_bf16 v[106:109], v[42:45], v[178:181], 0
	v_mfma_f32_16x16x32_bf16 v[158:161], v[38:41], v[58:61], v[158:161]
	v_mfma_f32_16x16x32_bf16 v[154:157], v[46:49], v[58:61], v[154:157]
	v_mfma_f32_16x16x32_bf16 v[142:145], v[38:41], v[66:69], v[142:145]
	v_mfma_f32_16x16x32_bf16 v[138:141], v[46:49], v[66:69], v[138:141]
	v_mfma_f32_16x16x32_bf16 v[126:129], v[38:41], v[174:177], v[126:129]
	v_mfma_f32_16x16x32_bf16 v[122:125], v[46:49], v[174:177], v[122:125]
	v_mfma_f32_16x16x32_bf16 v[110:113], v[38:41], v[182:185], v[110:113]
	v_mfma_f32_16x16x32_bf16 v[106:109], v[46:49], v[182:185], v[106:109]
	s_barrier
	v_mbcnt_lo_u32_b32 v250, -1, 0
	v_mbcnt_hi_u32_b32 v250, -1, v250
	v_lshlrev_b32_e32 v250, 4, v250
	s_lshl_b32 s32, s3, 10
	s_add_u32 s90, s8, s32
	s_addc_u32 s91, s9, 0
	s_add_u32 s92, s10, s32
	s_addc_u32 s93, s11, 0
	s_mov_b32 m0, 0x20840
	s_nop 0
	global_load_lds_dwordx4 v250, s[90:91]
	s_mov_b32 m0, 0x20c40
	s_nop 0
	global_load_lds_dwordx4 v250, s[92:93]
	s_add_i32 s68, 0, 0x14000
	s_add_i32 s4, s67, s52
	v_add_u32_e32 v1, s68, v191
	v_lshl_add_u64 v[214:215], s[46:47], 0, v[164:165]
	s_mov_b32 m0, s4
	ds_read_b128 v[186:189], v1
	ds_read_b128 v[208:211], v1 offset:1024
	ds_read_b128 v[222:225], v1 offset:2048
	ds_read_b128 v[226:229], v1 offset:3072
	global_load_lds_dwordx4 v[214:215], off
	v_lshl_add_u64 v[238:239], s[46:47], 0, v[162:163]
	s_add_i32 m0, s4, 0x2000
	s_nop 0
	global_load_lds_dwordx4 v[238:239], off
	s_barrier
	s_waitcnt lgkmcnt(0)
	s_waitcnt lgkmcnt(0)
	v_mfma_f32_16x16x32_bf16 v[150:153], v[186:189], v[50:53], 0
	v_mfma_f32_16x16x32_bf16 v[50:53], v[222:225], v[50:53], 0
	v_mfma_f32_16x16x32_bf16 v[150:153], v[208:211], v[58:61], v[150:153]
	v_mfma_f32_16x16x32_bf16 v[50:53], v[226:229], v[58:61], v[50:53]
	v_mfma_f32_16x16x32_bf16 v[58:61], v[186:189], v[62:65], 0
	v_mfma_f32_16x16x32_bf16 v[62:65], v[222:225], v[62:65], 0
	v_mfma_f32_16x16x32_bf16 v[114:117], v[222:225], v[170:173], 0
	v_mfma_f32_16x16x32_bf16 v[102:105], v[186:189], v[178:181], 0
	v_mfma_f32_16x16x32_bf16 v[98:101], v[222:225], v[178:181], 0
	v_mfma_f32_16x16x32_bf16 v[58:61], v[208:211], v[66:69], v[58:61]
	v_mfma_f32_16x16x32_bf16 v[62:65], v[226:229], v[66:69], v[62:65]
	v_mfma_f32_16x16x32_bf16 v[66:69], v[186:189], v[170:173], 0
	v_mfma_f32_16x16x32_bf16 v[114:117], v[226:229], v[174:177], v[114:117]
	v_mfma_f32_16x16x32_bf16 v[102:105], v[208:211], v[182:185], v[102:105]
	v_mfma_f32_16x16x32_bf16 v[98:101], v[226:229], v[182:185], v[98:101]
	v_mfma_f32_16x16x32_bf16 v[66:69], v[208:211], v[174:177], v[66:69]
	s_mov_b32 m0, s53
	v_lshl_add_u64 v[240:241], s[48:49], 0, v[164:165]
	s_barrier
	ds_read_b128 v[118:121], v206 offset:16384
	ds_read_b128 v[130:133], v206 offset:17408
	ds_read_b128 v[134:137], v206 offset:18432
	ds_read_b128 v[146:149], v206 offset:19456
	ds_read_b128 v[170:173], v206 offset:20480
	ds_read_b128 v[174:177], v206 offset:21504
	ds_read_b128 v[178:181], v206 offset:22528
	ds_read_b128 v[182:185], v206 offset:23552
	global_load_lds_dwordx4 v[240:241], off
	v_lshl_add_u64 v[242:243], s[48:49], 0, v[162:163]
	s_mov_b32 m0, s54
	s_nop 0
	global_load_lds_dwordx4 v[242:243], off
	s_barrier
	s_waitcnt lgkmcnt(0)
	s_waitcnt lgkmcnt(0)
	v_mfma_f32_16x16x32_bf16 v[94:97], v[34:37], v[118:121], 0
	v_mfma_f32_16x16x32_bf16 v[90:93], v[42:45], v[118:121], 0
	v_mfma_f32_16x16x32_bf16 v[78:81], v[34:37], v[134:137], 0
	v_mfma_f32_16x16x32_bf16 v[74:77], v[42:45], v[134:137], 0
	v_mfma_f32_16x16x32_bf16 v[30:33], v[34:37], v[170:173], 0
	v_mfma_f32_16x16x32_bf16 v[26:29], v[42:45], v[170:173], 0
	v_mfma_f32_16x16x32_bf16 v[14:17], v[34:37], v[178:181], 0
	v_mfma_f32_16x16x32_bf16 v[10:13], v[42:45], v[178:181], 0
	v_mfma_f32_16x16x32_bf16 v[94:97], v[38:41], v[130:133], v[94:97]
	v_mfma_f32_16x16x32_bf16 v[90:93], v[46:49], v[130:133], v[90:93]
	v_mfma_f32_16x16x32_bf16 v[78:81], v[38:41], v[146:149], v[78:81]
	v_mfma_f32_16x16x32_bf16 v[74:77], v[46:49], v[146:149], v[74:77]
	v_mfma_f32_16x16x32_bf16 v[30:33], v[38:41], v[174:177], v[30:33]
	v_mfma_f32_16x16x32_bf16 v[26:29], v[46:49], v[174:177], v[26:29]
	v_mfma_f32_16x16x32_bf16 v[14:17], v[38:41], v[182:185], v[14:17]
	v_mfma_f32_16x16x32_bf16 v[10:13], v[46:49], v[182:185], v[10:13]
	s_barrier
	s_add_u32 s4, s46, 0x40000
	s_addc_u32 s5, s47, 0
	s_add_i32 s67, s68, s52
	v_lshl_add_u64 v[34:35], s[4:5], 0, v[164:165]
	s_mov_b32 m0, s67
	s_nop 0
	global_load_lds_dwordx4 v[34:35], off
	v_lshl_add_u64 v[34:35], s[4:5], 0, v[162:163]
	s_add_i32 m0, s67, 0x2000
	s_nop 0
	global_load_lds_dwordx4 v[34:35], off
	s_waitcnt vmcnt(6)
	s_barrier
	v_mfma_f32_16x16x32_bf16 v[22:25], v[186:189], v[170:173], 0
	v_mfma_f32_16x16x32_bf16 v[18:21], v[222:225], v[170:173], 0
	v_mfma_f32_16x16x32_bf16 v[6:9], v[186:189], v[178:181], 0
	v_mfma_f32_16x16x32_bf16 v[2:5], v[222:225], v[178:181], 0
	v_mfma_f32_16x16x32_bf16 v[34:37], v[186:189], v[118:121], 0
	v_mfma_f32_16x16x32_bf16 v[38:41], v[222:225], v[118:121], 0
	v_mfma_f32_16x16x32_bf16 v[42:45], v[186:189], v[134:137], 0
	v_mfma_f32_16x16x32_bf16 v[46:49], v[222:225], v[134:137], 0
	v_mfma_f32_16x16x32_bf16 v[22:25], v[208:211], v[174:177], v[22:25]
	v_mfma_f32_16x16x32_bf16 v[18:21], v[226:229], v[174:177], v[18:21]
	v_mfma_f32_16x16x32_bf16 v[6:9], v[208:211], v[182:185], v[6:9]
	v_mfma_f32_16x16x32_bf16 v[2:5], v[226:229], v[182:185], v[2:5]
	v_mfma_f32_16x16x32_bf16 v[34:37], v[208:211], v[130:133], v[34:37]
	v_mfma_f32_16x16x32_bf16 v[38:41], v[226:229], v[130:133], v[38:41]
	v_mfma_f32_16x16x32_bf16 v[42:45], v[208:211], v[146:149], v[42:45]
	v_mfma_f32_16x16x32_bf16 v[46:49], v[226:229], v[146:149], v[46:49]
	s_add_i32 s67, 0, 0x18000
	v_add_u32_e32 v1, s67, v191
	s_barrier
	ds_read_b128 v[54:57], v1
	ds_read_b128 v[70:73], v1 offset:1024
	ds_read_b128 v[82:85], v1 offset:2048
	ds_read_b128 v[86:89], v1 offset:3072
	s_add_u32 s4, s48, 0x40000
	s_addc_u32 s5, s49, 0
	s_mov_b32 m0, s55
	v_lshl_add_u64 v[134:135], s[4:5], 0, v[164:165]
	ds_read_b128 v[118:121], v206 offset:32768
	ds_read_b128 v[130:133], v206 offset:33792
	ds_read_b128 v[170:173], v206 offset:34816
	ds_read_b128 v[174:177], v206 offset:35840
	ds_read_b128 v[178:181], v206 offset:36864
	ds_read_b128 v[182:185], v206 offset:37888
	ds_read_b128 v[186:189], v206 offset:38912
	ds_read_b128 v[208:211], v206 offset:39936
	global_load_lds_dwordx4 v[134:135], off
	v_lshl_add_u64 v[134:135], s[4:5], 0, v[162:163]
	s_mov_b32 m0, s56
	s_nop 0
	global_load_lds_dwordx4 v[134:135], off
	s_waitcnt lgkmcnt(8)
	s_barrier
	s_waitcnt lgkmcnt(0)
	s_waitcnt lgkmcnt(0)
	v_mfma_f32_16x16x32_bf16 v[134:137], v[54:57], v[118:121], v[158:161]
	v_mfma_f32_16x16x32_bf16 v[158:161], v[70:73], v[130:133], v[134:137]
	v_mfma_f32_16x16x32_bf16 v[134:137], v[82:85], v[118:121], v[154:157]
	v_mfma_f32_16x16x32_bf16 v[154:157], v[86:89], v[130:133], v[134:137]
	v_mfma_f32_16x16x32_bf16 v[134:137], v[54:57], v[170:173], v[142:145]
	v_mfma_f32_16x16x32_bf16 v[142:145], v[70:73], v[174:177], v[134:137]
	v_mfma_f32_16x16x32_bf16 v[134:137], v[82:85], v[170:173], v[138:141]
	v_mfma_f32_16x16x32_bf16 v[126:129], v[54:57], v[178:181], v[126:129]
	v_mfma_f32_16x16x32_bf16 v[122:125], v[82:85], v[178:181], v[122:125]
	v_mfma_f32_16x16x32_bf16 v[110:113], v[54:57], v[186:189], v[110:113]
	v_mfma_f32_16x16x32_bf16 v[106:109], v[82:85], v[186:189], v[106:109]
	v_mfma_f32_16x16x32_bf16 v[138:141], v[86:89], v[174:177], v[134:137]
	v_mfma_f32_16x16x32_bf16 v[126:129], v[70:73], v[182:185], v[126:129]
	v_mfma_f32_16x16x32_bf16 v[122:125], v[86:89], v[182:185], v[122:125]
	v_mfma_f32_16x16x32_bf16 v[110:113], v[70:73], v[208:211], v[110:113]
	v_mfma_f32_16x16x32_bf16 v[106:109], v[86:89], v[208:211], v[106:109]
	s_barrier
	s_add_i32 s48, 0, 0x1c000
	s_add_i32 s4, s67, s52
	v_add_u32_e32 v1, s48, v191
	v_lshl_add_u64 v[134:135], v[214:215], 0, s[22:23]
	s_mov_b32 m0, s4
	ds_read_b128 v[222:225], v1
	ds_read_b128 v[226:229], v1 offset:1024
	ds_read_b128 v[230:233], v1 offset:2048
	ds_read_b128 v[234:237], v1 offset:3072
	global_load_lds_dwordx4 v[134:135], off
	v_lshl_add_u64 v[134:135], v[238:239], 0, s[22:23]
	s_add_i32 m0, s4, 0x2000
	s_nop 0
	global_load_lds_dwordx4 v[134:135], off
	s_barrier
	s_waitcnt lgkmcnt(0)
	s_waitcnt lgkmcnt(0)
	v_mfma_f32_16x16x32_bf16 v[50:53], v[230:233], v[118:121], v[50:53]
	v_mfma_f32_16x16x32_bf16 v[134:137], v[222:225], v[118:121], v[150:153]
	v_mfma_f32_16x16x32_bf16 v[146:149], v[234:237], v[130:133], v[50:53]
	v_mfma_f32_16x16x32_bf16 v[50:53], v[222:225], v[170:173], v[58:61]
	v_mfma_f32_16x16x32_bf16 v[150:153], v[226:229], v[130:133], v[134:137]
	v_mfma_f32_16x16x32_bf16 v[134:137], v[226:229], v[174:177], v[50:53]
	v_mfma_f32_16x16x32_bf16 v[50:53], v[230:233], v[170:173], v[62:65]
	v_mfma_f32_16x16x32_bf16 v[130:133], v[234:237], v[174:177], v[50:53]
	v_mfma_f32_16x16x32_bf16 v[50:53], v[222:225], v[178:181], v[66:69]
	v_mfma_f32_16x16x32_bf16 v[118:121], v[226:229], v[182:185], v[50:53]
	v_mfma_f32_16x16x32_bf16 v[50:53], v[230:233], v[178:181], v[114:117]
	v_mfma_f32_16x16x32_bf16 v[114:117], v[234:237], v[182:185], v[50:53]
	v_mfma_f32_16x16x32_bf16 v[50:53], v[222:225], v[186:189], v[102:105]
	v_mfma_f32_16x16x32_bf16 v[102:105], v[226:229], v[208:211], v[50:53]
	v_mfma_f32_16x16x32_bf16 v[50:53], v[230:233], v[186:189], v[98:101]
	v_mfma_f32_16x16x32_bf16 v[98:101], v[234:237], v[208:211], v[50:53]
	s_mov_b32 m0, s58
	v_lshl_add_u64 v[186:187], v[240:241], 0, s[22:23]
	s_barrier
	s_nop 2
	ds_read_b128 v[50:53], v206 offset:49152
	ds_read_b128 v[58:61], v206 offset:50176
	ds_read_b128 v[62:65], v206 offset:51200
	ds_read_b128 v[66:69], v206 offset:52224
	ds_read_b128 v[170:173], v206 offset:53248
	ds_read_b128 v[174:177], v206 offset:54272
	ds_read_b128 v[178:181], v206 offset:55296
	ds_read_b128 v[182:185], v206 offset:56320
	global_load_lds_dwordx4 v[186:187], off
	v_lshl_add_u64 v[186:187], v[242:243], 0, s[22:23]
	s_mov_b32 m0, s59
	s_nop 0
	global_load_lds_dwordx4 v[186:187], off
	s_barrier
	s_waitcnt lgkmcnt(0)
	s_waitcnt lgkmcnt(0)
	v_mfma_f32_16x16x32_bf16 v[94:97], v[54:57], v[50:53], v[94:97]
	v_mfma_f32_16x16x32_bf16 v[90:93], v[82:85], v[50:53], v[90:93]
	v_mfma_f32_16x16x32_bf16 v[78:81], v[54:57], v[62:65], v[78:81]
	v_mfma_f32_16x16x32_bf16 v[74:77], v[82:85], v[62:65], v[74:77]
	v_mfma_f32_16x16x32_bf16 v[30:33], v[54:57], v[170:173], v[30:33]
	v_mfma_f32_16x16x32_bf16 v[26:29], v[82:85], v[170:173], v[26:29]
	v_mfma_f32_16x16x32_bf16 v[14:17], v[54:57], v[178:181], v[14:17]
	v_mfma_f32_16x16x32_bf16 v[10:13], v[82:85], v[178:181], v[10:13]
	v_mfma_f32_16x16x32_bf16 v[94:97], v[70:73], v[58:61], v[94:97]
	v_mfma_f32_16x16x32_bf16 v[90:93], v[86:89], v[58:61], v[90:93]
	v_mfma_f32_16x16x32_bf16 v[78:81], v[70:73], v[66:69], v[78:81]
	v_mfma_f32_16x16x32_bf16 v[74:77], v[86:89], v[66:69], v[74:77]
	v_mfma_f32_16x16x32_bf16 v[30:33], v[70:73], v[174:177], v[30:33]
	v_mfma_f32_16x16x32_bf16 v[26:29], v[86:89], v[174:177], v[26:29]
	v_mfma_f32_16x16x32_bf16 v[14:17], v[70:73], v[182:185], v[14:17]
	v_mfma_f32_16x16x32_bf16 v[10:13], v[86:89], v[182:185], v[10:13]
	s_barrier
	s_add_u32 s4, s46, 0x40080
	s_addc_u32 s5, s47, 0
	s_add_i32 s46, s48, s52
	v_lshl_add_u64 v[54:55], s[4:5], 0, v[164:165]
	s_mov_b32 m0, s46
	s_nop 0
	global_load_lds_dwordx4 v[54:55], off
	v_lshl_add_u64 v[54:55], s[4:5], 0, v[162:163]
	s_add_i32 m0, s46, 0x2000
	s_nop 0
	global_load_lds_dwordx4 v[54:55], off
	s_waitcnt vmcnt(6)
	s_barrier
	v_mfma_f32_16x16x32_bf16 v[34:37], v[222:225], v[50:53], v[34:37]
	v_mfma_f32_16x16x32_bf16 v[86:89], v[226:229], v[58:61], v[34:37]
	v_mfma_f32_16x16x32_bf16 v[34:37], v[230:233], v[50:53], v[38:41]
	v_mfma_f32_16x16x32_bf16 v[82:85], v[234:237], v[58:61], v[34:37]
	v_mfma_f32_16x16x32_bf16 v[34:37], v[222:225], v[62:65], v[42:45]
	v_mfma_f32_16x16x32_bf16 v[70:73], v[226:229], v[66:69], v[34:37]
	v_mfma_f32_16x16x32_bf16 v[34:37], v[230:233], v[62:65], v[46:49]
	v_mfma_f32_16x16x32_bf16 v[22:25], v[222:225], v[170:173], v[22:25]
	v_mfma_f32_16x16x32_bf16 v[18:21], v[230:233], v[170:173], v[18:21]
	v_mfma_f32_16x16x32_bf16 v[6:9], v[222:225], v[178:181], v[6:9]
	v_mfma_f32_16x16x32_bf16 v[2:5], v[230:233], v[178:181], v[2:5]
	v_mfma_f32_16x16x32_bf16 v[54:57], v[234:237], v[66:69], v[34:37]
	v_mfma_f32_16x16x32_bf16 v[22:25], v[226:229], v[174:177], v[22:25]
	v_mfma_f32_16x16x32_bf16 v[18:21], v[234:237], v[174:177], v[18:21]
	v_mfma_f32_16x16x32_bf16 v[6:9], v[226:229], v[182:185], v[6:9]
	v_mfma_f32_16x16x32_bf16 v[2:5], v[234:237], v[182:185], v[2:5]
	s_add_i32 s66, s66, 2
	s_add_u32 s64, s64, 0x100
	s_addc_u32 s65, s65, 0
	s_cmp_gt_u32 s66, 13
	s_mov_b64 s[4:5], s[36:37]
	s_barrier

.LBB0_394:
	s_or_b64 exec, exec, s[4:5]
	v_add_lshl_u32 v2, v46, v138, 1
	v_cvt_pk_bf16_f32 v8, v8, v9
	v_cvt_pk_bf16_f32 v9, v10, v11
	buffer_store_dwordx4 v[6:9], v2, s[28:31], 0 offen sc1
	s_and_b64 vcc, exec, s[52:53]
	s_cbranch_vccnz .LBB0_813
.LBB0_395:
	s_add_i32 s66, s66, 1
	s_mov_b64 s[36:37], s[20:21]
	s_mul_i32 s20, s66, s26
	s_add_i32 s42, s20, s2
	s_cmpk_gt_i32 s42, 0x3ff
	s_cselect_b64 s[52:53], -1, 0
	s_lshl_b32 s20, s42, 3
	s_and_b32 s20, s20, 56
	s_bfe_u32 s21, s42, 0x30003
	s_mov_b32 s3, s67
	s_or_b32 s67, s20, s21
	s_mov_b32 s27, s50
	s_ashr_i32 s50, s42, 6
	s_lshl_b32 s20, s67, 19
	s_mov_b64 s[4:5], s[48:49]
	s_add_u32 s48, s18, s20
	s_addc_u32 s49, s19, 0
	s_ashr_i32 s51, s50, 31
	s_lshl_b64 s[20:21], s[50:51], 19
	s_add_u32 s20, s16, s20
	s_addc_u32 s21, s17, s21
	s_cmpk_lt_i32 s42, 0x400
	s_cselect_b32 s46, s49, s5
	s_cselect_b32 s47, s48, s4
	s_cselect_b32 s51, s21, s37
	s_cselect_b32 s54, s20, s36
	s_add_u32 s55, s36, 0x100
	s_addc_u32 s56, s37, 0
	s_mov_b32 s57, -2
	s_add_u32 s36, s4, 0x100
	s_addc_u32 s37, s5, 0
	s_add_i32 s68, 0, 0x10000
	v_add_u32_e32 v30, s68, v204
	ds_read_b128 v[14:17], v30
	ds_read_b128 v[22:25], v30 offset:1024
	ds_read_b128 v[26:29], v30 offset:2048
	ds_read_b128 v[30:33], v30 offset:3072
	s_cmp_eq_u32 s57, 12
	s_cselect_b32 s45, s46, s37
	s_cselect_b32 s44, s47, s36
	s_cselect_b32 s43, s51, s56
	s_cselect_b32 s42, s54, s55
	v_lshl_add_u64 v[178:179], s[4:5], 0, v[188:189]
	s_add_i32 m0, s60, 0xc000
	ds_read_b128 v[38:41], v209
	ds_read_b128 v[42:45], v209 offset:1024
	ds_read_b128 v[46:49], v209 offset:2048
	ds_read_b128 v[54:57], v209 offset:3072
	ds_read_b128 v[58:61], v209 offset:4096
	ds_read_b128 v[62:65], v209 offset:5120
	ds_read_b128 v[66:69], v209 offset:6144
	ds_read_b128 v[70:73], v209 offset:7168
	global_load_lds_dwordx4 v[178:179], off
	v_lshl_add_u64 v[178:179], s[4:5], 0, v[186:187]
	s_add_i32 m0, s60, 0xe000
	s_nop 0
	global_load_lds_dwordx4 v[178:179], off
	s_waitcnt lgkmcnt(8)
	s_barrier
	s_waitcnt lgkmcnt(0)
	s_waitcnt lgkmcnt(0)
	v_mfma_f32_16x16x32_bf16 v[174:177], v[14:17], v[38:41], 0
	v_mfma_f32_16x16x32_bf16 v[170:173], v[26:29], v[38:41], 0
	v_mfma_f32_16x16x32_bf16 v[158:161], v[14:17], v[46:49], 0
	v_mfma_f32_16x16x32_bf16 v[154:157], v[26:29], v[46:49], 0
	v_mfma_f32_16x16x32_bf16 v[142:145], v[14:17], v[58:61], 0
	v_mfma_f32_16x16x32_bf16 v[138:141], v[26:29], v[58:61], 0
	v_mfma_f32_16x16x32_bf16 v[126:129], v[14:17], v[66:69], 0
	v_mfma_f32_16x16x32_bf16 v[122:125], v[26:29], v[66:69], 0
	v_mfma_f32_16x16x32_bf16 v[174:177], v[22:25], v[42:45], v[174:177]
	v_mfma_f32_16x16x32_bf16 v[170:173], v[30:33], v[42:45], v[170:173]
	v_mfma_f32_16x16x32_bf16 v[158:161], v[22:25], v[54:57], v[158:161]
	v_mfma_f32_16x16x32_bf16 v[154:157], v[30:33], v[54:57], v[154:157]
	v_mfma_f32_16x16x32_bf16 v[142:145], v[22:25], v[62:65], v[142:145]
	v_mfma_f32_16x16x32_bf16 v[138:141], v[30:33], v[62:65], v[138:141]
	v_mfma_f32_16x16x32_bf16 v[126:129], v[22:25], v[70:73], v[126:129]
	v_mfma_f32_16x16x32_bf16 v[122:125], v[30:33], v[70:73], v[122:125]
	s_barrier
	v_mbcnt_lo_u32_b32 v250, -1, 0
	v_mbcnt_hi_u32_b32 v250, -1, v250
	v_lshlrev_b32_e32 v250, 4, v250
	s_lshl_b32 s32, s27, 10
	s_add_u32 s90, s10, s32
	s_addc_u32 s91, s11, 0
	s_add_u32 s92, s12, s32
	s_addc_u32 s93, s13, 0
	s_and_b32 s32, s27, 3
	s_lshl_b32 s32, s32, 10
	s_add_u32 s98, s14, s32
	s_addc_u32 s99, s15, 0
	s_mov_b32 m0, 0x20840
	s_nop 0
	global_load_lds_dwordx4 v250, s[90:91]
	s_mov_b32 m0, 0x20c40
	s_nop 0
	global_load_lds_dwordx4 v250, s[92:93]
	s_mov_b32 m0, 0x21040
	s_nop 0
	global_load_lds_dwordx4 v250, s[98:99]
	s_add_i32 s69, 0, 0x14000
	v_add_u32_e32 v210, s69, v204
	s_add_i32 s4, s68, s59
	ds_read_b128 v[178:181], v210
	ds_read_b128 v[190:193], v210 offset:1024
	ds_read_b128 v[200:203], v210 offset:2048
	ds_read_b128 v[222:225], v210 offset:3072
	v_lshl_add_u64 v[210:211], s[42:43], 0, v[184:185]
	s_mov_b32 m0, s4
	v_lshl_add_u64 v[214:215], s[42:43], 0, v[182:183]
	global_load_lds_dwordx4 v[210:211], off
	s_add_i32 m0, s4, 0x2000
	s_nop 0
	global_load_lds_dwordx4 v[214:215], off
	s_barrier
	s_waitcnt lgkmcnt(0)
	s_waitcnt lgkmcnt(0)
	v_mfma_f32_16x16x32_bf16 v[166:169], v[178:181], v[38:41], 0
	v_mfma_f32_16x16x32_bf16 v[38:41], v[200:203], v[38:41], 0
	v_mfma_f32_16x16x32_bf16 v[166:169], v[190:193], v[42:45], v[166:169]
	v_mfma_f32_16x16x32_bf16 v[38:41], v[222:225], v[42:45], v[38:41]
	v_mfma_f32_16x16x32_bf16 v[42:45], v[178:181], v[46:49], 0
	v_mfma_f32_16x16x32_bf16 v[46:49], v[200:203], v[46:49], 0
	v_mfma_f32_16x16x32_bf16 v[42:45], v[190:193], v[54:57], v[42:45]
	v_mfma_f32_16x16x32_bf16 v[46:49], v[222:225], v[54:57], v[46:49]
	v_mfma_f32_16x16x32_bf16 v[54:57], v[178:181], v[58:61], 0
	v_mfma_f32_16x16x32_bf16 v[58:61], v[200:203], v[58:61], 0
	v_mfma_f32_16x16x32_bf16 v[54:57], v[190:193], v[62:65], v[54:57]
	v_mfma_f32_16x16x32_bf16 v[58:61], v[222:225], v[62:65], v[58:61]
	v_mfma_f32_16x16x32_bf16 v[62:65], v[178:181], v[66:69], 0
	v_mfma_f32_16x16x32_bf16 v[66:69], v[200:203], v[66:69], 0
	v_mfma_f32_16x16x32_bf16 v[62:65], v[190:193], v[70:73], v[62:65]
	v_mfma_f32_16x16x32_bf16 v[66:69], v[222:225], v[70:73], v[66:69]
	s_mov_b32 m0, s60
	v_lshl_add_u64 v[242:243], s[44:45], 0, v[184:185]
	s_barrier
	ds_read_b128 v[70:73], v209 offset:16384
	ds_read_b128 v[114:117], v209 offset:17408
	ds_read_b128 v[118:121], v209 offset:18432
	ds_read_b128 v[130:133], v209 offset:19456
	ds_read_b128 v[134:137], v209 offset:20480
	ds_read_b128 v[146:149], v209 offset:21504
	ds_read_b128 v[150:153], v209 offset:22528
	ds_read_b128 v[162:165], v209 offset:23552
	global_load_lds_dwordx4 v[242:243], off
	v_lshl_add_u64 v[244:245], s[44:45], 0, v[182:183]
	s_mov_b32 m0, s61
	s_nop 0
	global_load_lds_dwordx4 v[244:245], off
	s_barrier
	s_waitcnt lgkmcnt(0)
	s_waitcnt lgkmcnt(0)
	v_mfma_f32_16x16x32_bf16 v[110:113], v[14:17], v[70:73], 0
	v_mfma_f32_16x16x32_bf16 v[106:109], v[26:29], v[70:73], 0
	v_mfma_f32_16x16x32_bf16 v[94:97], v[14:17], v[118:121], 0
	v_mfma_f32_16x16x32_bf16 v[90:93], v[26:29], v[118:121], 0
	v_mfma_f32_16x16x32_bf16 v[78:81], v[14:17], v[134:137], 0
	v_mfma_f32_16x16x32_bf16 v[74:77], v[26:29], v[134:137], 0
	v_mfma_f32_16x16x32_bf16 v[10:13], v[26:29], v[150:153], 0
	v_mfma_f32_16x16x32_bf16 v[110:113], v[22:25], v[114:117], v[110:113]
	v_mfma_f32_16x16x32_bf16 v[106:109], v[30:33], v[114:117], v[106:109]
	v_mfma_f32_16x16x32_bf16 v[94:97], v[22:25], v[130:133], v[94:97]
	v_mfma_f32_16x16x32_bf16 v[90:93], v[30:33], v[130:133], v[90:93]
	v_mfma_f32_16x16x32_bf16 v[78:81], v[22:25], v[146:149], v[78:81]
	v_mfma_f32_16x16x32_bf16 v[74:77], v[30:33], v[146:149], v[74:77]
	v_mfma_f32_16x16x32_bf16 v[14:17], v[14:17], v[150:153], 0
	v_mfma_f32_16x16x32_bf16 v[10:13], v[30:33], v[162:165], v[10:13]
	v_mfma_f32_16x16x32_bf16 v[14:17], v[22:25], v[162:165], v[14:17]
	s_barrier
	s_add_u32 s4, s42, 0x40000
	s_addc_u32 s5, s43, 0
	s_add_i32 s68, s69, s59
	v_lshl_add_u64 v[18:19], s[4:5], 0, v[184:185]
	s_mov_b32 m0, s68
	s_nop 0
	global_load_lds_dwordx4 v[18:19], off
	v_lshl_add_u64 v[18:19], s[4:5], 0, v[182:183]
	s_add_i32 m0, s68, 0x2000
	s_nop 0
	global_load_lds_dwordx4 v[18:19], off
	s_waitcnt vmcnt(6)
	s_barrier
	v_mfma_f32_16x16x32_bf16 v[18:21], v[178:181], v[70:73], 0
	v_mfma_f32_16x16x32_bf16 v[22:25], v[190:193], v[114:117], v[18:21]
	v_mfma_f32_16x16x32_bf16 v[18:21], v[200:203], v[70:73], 0
	v_mfma_f32_16x16x32_bf16 v[26:29], v[222:225], v[114:117], v[18:21]
	v_mfma_f32_16x16x32_bf16 v[18:21], v[178:181], v[118:121], 0
	v_mfma_f32_16x16x32_bf16 v[30:33], v[190:193], v[130:133], v[18:21]
	v_mfma_f32_16x16x32_bf16 v[18:21], v[200:203], v[118:121], 0
	v_mfma_f32_16x16x32_bf16 v[70:73], v[222:225], v[130:133], v[18:21]
	v_mfma_f32_16x16x32_bf16 v[18:21], v[178:181], v[134:137], 0
	v_mfma_f32_16x16x32_bf16 v[50:53], v[190:193], v[146:149], v[18:21]
	v_mfma_f32_16x16x32_bf16 v[18:21], v[200:203], v[134:137], 0
	v_mfma_f32_16x16x32_bf16 v[6:9], v[178:181], v[150:153], 0
	v_mfma_f32_16x16x32_bf16 v[2:5], v[200:203], v[150:153], 0
	v_mfma_f32_16x16x32_bf16 v[34:37], v[222:225], v[146:149], v[18:21]
	v_mfma_f32_16x16x32_bf16 v[6:9], v[190:193], v[162:165], v[6:9]
	v_mfma_f32_16x16x32_bf16 v[2:5], v[222:225], v[162:165], v[2:5]
	s_add_i32 s68, 0, 0x18000
	v_add_u32_e32 v98, s68, v204
	s_barrier
	ds_read_b128 v[18:21], v98
	ds_read_b128 v[82:85], v98 offset:1024
	ds_read_b128 v[86:89], v98 offset:2048
	ds_read_b128 v[98:101], v98 offset:3072
	s_add_u32 s4, s44, 0x40000
	s_addc_u32 s5, s45, 0
	s_mov_b32 m0, s62
	v_lshl_add_u64 v[134:135], s[4:5], 0, v[184:185]
	ds_read_b128 v[102:105], v209 offset:32768
	ds_read_b128 v[114:117], v209 offset:33792
	ds_read_b128 v[118:121], v209 offset:34816
	ds_read_b128 v[130:133], v209 offset:35840
	ds_read_b128 v[178:181], v209 offset:36864
	ds_read_b128 v[190:193], v209 offset:37888
	ds_read_b128 v[200:203], v209 offset:38912
	ds_read_b128 v[222:225], v209 offset:39936
	global_load_lds_dwordx4 v[134:135], off
	v_lshl_add_u64 v[134:135], s[4:5], 0, v[182:183]
	s_mov_b32 m0, s63
	s_nop 0
	global_load_lds_dwordx4 v[134:135], off
	s_waitcnt lgkmcnt(8)
	s_barrier
	s_waitcnt lgkmcnt(0)
	s_waitcnt lgkmcnt(0)
	v_mfma_f32_16x16x32_bf16 v[134:137], v[18:21], v[102:105], v[174:177]
	v_mfma_f32_16x16x32_bf16 v[174:177], v[82:85], v[114:117], v[134:137]
	v_mfma_f32_16x16x32_bf16 v[134:137], v[86:89], v[102:105], v[170:173]
	v_mfma_f32_16x16x32_bf16 v[170:173], v[98:101], v[114:117], v[134:137]
	v_mfma_f32_16x16x32_bf16 v[134:137], v[18:21], v[118:121], v[158:161]
	v_mfma_f32_16x16x32_bf16 v[158:161], v[82:85], v[130:133], v[134:137]
	v_mfma_f32_16x16x32_bf16 v[134:137], v[86:89], v[118:121], v[154:157]
	v_mfma_f32_16x16x32_bf16 v[154:157], v[98:101], v[130:133], v[134:137]
	v_mfma_f32_16x16x32_bf16 v[134:137], v[18:21], v[178:181], v[142:145]
	v_mfma_f32_16x16x32_bf16 v[142:145], v[82:85], v[190:193], v[134:137]
	v_mfma_f32_16x16x32_bf16 v[134:137], v[86:89], v[178:181], v[138:141]
	v_mfma_f32_16x16x32_bf16 v[126:129], v[18:21], v[200:203], v[126:129]
	v_mfma_f32_16x16x32_bf16 v[122:125], v[86:89], v[200:203], v[122:125]
	v_mfma_f32_16x16x32_bf16 v[138:141], v[98:101], v[190:193], v[134:137]
	v_mfma_f32_16x16x32_bf16 v[126:129], v[82:85], v[222:225], v[126:129]
	v_mfma_f32_16x16x32_bf16 v[122:125], v[98:101], v[222:225], v[122:125]
	s_barrier
	s_add_i32 s44, 0, 0x1c000
	v_add_u32_e32 v134, s44, v204
	s_add_i32 s4, s68, s59
	ds_read_b128 v[226:229], v134
	ds_read_b128 v[230:233], v134 offset:1024
	ds_read_b128 v[234:237], v134 offset:2048
	ds_read_b128 v[238:241], v134 offset:3072
	v_lshl_add_u64 v[134:135], v[210:211], 0, s[22:23]
	s_mov_b32 m0, s4
	s_nop 0
	global_load_lds_dwordx4 v[134:135], off
	v_lshl_add_u64 v[134:135], v[214:215], 0, s[22:23]
	s_add_i32 m0, s4, 0x2000
	s_nop 0
	global_load_lds_dwordx4 v[134:135], off
	s_barrier
	s_waitcnt lgkmcnt(0)
	s_waitcnt lgkmcnt(0)
	v_mfma_f32_16x16x32_bf16 v[38:41], v[234:237], v[102:105], v[38:41]
	v_mfma_f32_16x16x32_bf16 v[162:165], v[238:241], v[114:117], v[38:41]
	v_mfma_f32_16x16x32_bf16 v[38:41], v[226:229], v[118:121], v[42:45]
	v_mfma_f32_16x16x32_bf16 v[150:153], v[230:233], v[130:133], v[38:41]
	v_mfma_f32_16x16x32_bf16 v[38:41], v[234:237], v[118:121], v[46:49]
	v_mfma_f32_16x16x32_bf16 v[134:137], v[226:229], v[102:105], v[166:169]
	v_mfma_f32_16x16x32_bf16 v[146:149], v[238:241], v[130:133], v[38:41]
	v_mfma_f32_16x16x32_bf16 v[38:41], v[226:229], v[178:181], v[54:57]
	v_mfma_f32_16x16x32_bf16 v[166:169], v[230:233], v[114:117], v[134:137]
	v_mfma_f32_16x16x32_bf16 v[134:137], v[230:233], v[190:193], v[38:41]
	v_mfma_f32_16x16x32_bf16 v[38:41], v[234:237], v[178:181], v[58:61]
	v_mfma_f32_16x16x32_bf16 v[130:133], v[238:241], v[190:193], v[38:41]
	v_mfma_f32_16x16x32_bf16 v[38:41], v[226:229], v[200:203], v[62:65]
	v_mfma_f32_16x16x32_bf16 v[118:121], v[230:233], v[222:225], v[38:41]
	v_mfma_f32_16x16x32_bf16 v[38:41], v[234:237], v[200:203], v[66:69]
	v_mfma_f32_16x16x32_bf16 v[114:117], v[238:241], v[222:225], v[38:41]
	s_mov_b32 m0, s64
	v_lshl_add_u64 v[102:103], v[242:243], 0, s[22:23]
	s_barrier
	s_nop 2
	ds_read_b128 v[38:41], v209 offset:49152
	ds_read_b128 v[42:45], v209 offset:50176
	ds_read_b128 v[46:49], v209 offset:51200
	ds_read_b128 v[54:57], v209 offset:52224
	ds_read_b128 v[58:61], v209 offset:53248
	ds_read_b128 v[62:65], v209 offset:54272
	ds_read_b128 v[66:69], v209 offset:55296
	ds_read_b128 v[178:181], v209 offset:56320
	global_load_lds_dwordx4 v[102:103], off
	v_lshl_add_u64 v[102:103], v[244:245], 0, s[22:23]
	s_mov_b32 m0, s65
	s_nop 0
	global_load_lds_dwordx4 v[102:103], off
	s_barrier
	s_waitcnt lgkmcnt(0)
	s_waitcnt lgkmcnt(0)
	v_mfma_f32_16x16x32_bf16 v[102:105], v[18:21], v[38:41], v[110:113]
	v_mfma_f32_16x16x32_bf16 v[110:113], v[82:85], v[42:45], v[102:105]
	v_mfma_f32_16x16x32_bf16 v[102:105], v[86:89], v[38:41], v[106:109]
	v_mfma_f32_16x16x32_bf16 v[94:97], v[18:21], v[46:49], v[94:97]
	v_mfma_f32_16x16x32_bf16 v[90:93], v[86:89], v[46:49], v[90:93]
	v_mfma_f32_16x16x32_bf16 v[78:81], v[18:21], v[58:61], v[78:81]
	v_mfma_f32_16x16x32_bf16 v[74:77], v[86:89], v[58:61], v[74:77]
	v_mfma_f32_16x16x32_bf16 v[14:17], v[18:21], v[66:69], v[14:17]
	v_mfma_f32_16x16x32_bf16 v[10:13], v[86:89], v[66:69], v[10:13]
	v_mfma_f32_16x16x32_bf16 v[106:109], v[98:101], v[42:45], v[102:105]
	v_mfma_f32_16x16x32_bf16 v[94:97], v[82:85], v[54:57], v[94:97]
	v_mfma_f32_16x16x32_bf16 v[90:93], v[98:101], v[54:57], v[90:93]
	v_mfma_f32_16x16x32_bf16 v[78:81], v[82:85], v[62:65], v[78:81]
	v_mfma_f32_16x16x32_bf16 v[74:77], v[98:101], v[62:65], v[74:77]
	v_mfma_f32_16x16x32_bf16 v[18:21], v[82:85], v[178:181], v[14:17]
	v_mfma_f32_16x16x32_bf16 v[10:13], v[98:101], v[178:181], v[10:13]
	s_barrier
	s_add_u32 s4, s42, 0x40080
	s_addc_u32 s5, s43, 0
	s_add_i32 s42, s44, s59
	v_lshl_add_u64 v[14:15], s[4:5], 0, v[184:185]
	s_mov_b32 m0, s42
	s_nop 0
	global_load_lds_dwordx4 v[14:15], off
	v_lshl_add_u64 v[14:15], s[4:5], 0, v[182:183]
	s_add_i32 m0, s42, 0x2000
	s_nop 0
	global_load_lds_dwordx4 v[14:15], off
	s_waitcnt vmcnt(6)
	s_barrier
	v_mfma_f32_16x16x32_bf16 v[14:17], v[226:229], v[38:41], v[22:25]
	v_mfma_f32_16x16x32_bf16 v[102:105], v[230:233], v[42:45], v[14:17]
	v_mfma_f32_16x16x32_bf16 v[14:17], v[234:237], v[38:41], v[26:29]
	v_mfma_f32_16x16x32_bf16 v[98:101], v[238:241], v[42:45], v[14:17]
	v_mfma_f32_16x16x32_bf16 v[14:17], v[226:229], v[46:49], v[30:33]
	v_mfma_f32_16x16x32_bf16 v[86:89], v[230:233], v[54:57], v[14:17]
	v_mfma_f32_16x16x32_bf16 v[14:17], v[234:237], v[46:49], v[70:73]
	v_mfma_f32_16x16x32_bf16 v[82:85], v[238:241], v[54:57], v[14:17]
	v_mfma_f32_16x16x32_bf16 v[14:17], v[226:229], v[58:61], v[50:53]
	v_mfma_f32_16x16x32_bf16 v[50:53], v[230:233], v[62:65], v[14:17]
	v_mfma_f32_16x16x32_bf16 v[14:17], v[234:237], v[58:61], v[34:37]
	v_mfma_f32_16x16x32_bf16 v[6:9], v[226:229], v[66:69], v[6:9]
	v_mfma_f32_16x16x32_bf16 v[2:5], v[234:237], v[66:69], v[2:5]
	v_mfma_f32_16x16x32_bf16 v[34:37], v[238:241], v[62:65], v[14:17]
	v_mfma_f32_16x16x32_bf16 v[6:9], v[230:233], v[178:181], v[6:9]
	v_mfma_f32_16x16x32_bf16 v[2:5], v[238:241], v[178:181], v[2:5]
	s_add_i32 s57, s57, 2
	s_add_u32 s55, s55, 0x100
	s_addc_u32 s56, s56, 0
	s_cmp_gt_u32 s57, 13
	s_mov_b64 s[4:5], s[36:37]
	s_barrier

.LBB0_1097:
	v_lshrrev_b32_e32 v20, 1, v18
	v_and_b32_e32 v20, 24, v20
	v_and_b32_e32 v19, 15, v18
	v_lshlrev_b32_e32 v21, 1, v20
	v_lshlrev_b32_e32 v18, 2, v18
	s_lshl_b32 s3, s3, 5
	s_lshl_b32 s36, s27, 6
	v_lshl_or_b32 v21, v19, 6, v21
	s_lshl_b32 s27, s27, 13
	v_and_b32_e32 v18, 32, v18
	s_and_b32 s3, s3, 0x60
	s_add_i32 m0, s69, 0x18000
	v_lshl_add_u64 v[8:9], v[8:9], 0, s[22:23]
	v_bitop3_b32 v22, v21, s27, v18 bitop3:0xde
	s_lshl_b32 s27, s3, 7
	s_waitcnt vmcnt(4)
	s_barrier
	global_load_lds_dwordx4 v[8:9], off
	v_lshl_add_u64 v[6:7], v[6:7], 0, s[22:23]
	s_add_i32 m0, s69, 0x1a000
	s_add_i32 s73, s69, 0x8000
	s_add_i32 s75, s69, 0xa000
	global_load_lds_dwordx4 v[6:7], off
	v_lshl_add_u64 v[4:5], v[4:5], 0, s[22:23]
	s_mov_b32 m0, s73
	s_add_u32 s28, s54, 0x40080
	global_load_lds_dwordx4 v[4:5], off
	v_lshl_add_u64 v[2:3], v[2:3], 0, s[22:23]
	s_mov_b32 m0, s75
	s_addc_u32 s29, s55, 0
	global_load_lds_dwordx4 v[2:3], off
	s_add_i32 m0, s69, 0x1c000
	v_lshl_add_u64 v[2:3], s[28:29], 0, v[164:165]
	global_load_lds_dwordx4 v[2:3], off
	v_lshl_add_u64 v[2:3], s[28:29], 0, v[162:163]
	s_add_i32 m0, s69, 0x1e000
	v_or_b32_e32 v1, s36, v19
	global_load_lds_dwordx4 v[2:3], off
	v_lshlrev_b32_e32 v2, 13, v10
	v_and_b32_e32 v2, 0x7fffc000, v2
	v_lshl_add_u32 v2, v11, 10, v2
	s_addk_i32 s36, 0x80
	v_or_b32_e32 v2, v2, v12
	v_or_b32_e32 v172, s36, v19
	v_add_lshl_u32 v2, v2, v13, 1
	v_mov_b32_e32 v3, v0
	s_mov_b64 s[36:37], 0x40080
	v_lshl_add_u64 v[166:167], v[2:3], 0, s[36:37]
	v_lshlrev_b32_e32 v2, 13, v15
	v_and_b32_e32 v2, 0x7fffc000, v2
	v_lshl_add_u32 v2, v14, 10, v2
	v_or_b32_e32 v2, v2, v16
	s_waitcnt vmcnt(6)
	v_add_lshl_u32 v2, v2, v17, 1
	v_lshl_add_u64 v[168:169], v[2:3], 0, s[36:37]
	v_readlane_b32 s36, v252, 51
	v_bitop3_b32 v170, v21, s27, v18 bitop3:0xde
	v_or_b32_e32 v171, 32, v1
	v_or_b32_e32 v173, 32, v172
	s_and_b32 s29, s51, 0xffff
	s_mov_b32 s28, s50
	v_or_b32_e32 v174, s3, v20
	s_mov_b32 s76, 0
	v_add_u32_e32 v175, 0, v22
	s_mov_b32 s27, s36
	v_readlane_b32 s3, v254, 29
	s_barrier
	v_readlane_b32 s37, v252, 52
.LBB0_1098:
	s_add_i32 s76, s76, 1
	s_mov_b64 s[62:63], s[54:55]
	s_mul_i32 s54, s76, s26
	s_add_i32 s64, s54, s2
	s_cmpk_gt_i32 s64, 0x57f
	s_cselect_b64 s[60:61], -1, 0
	s_lshl_b32 s54, s64, 3
	s_and_b32 s54, s54, 56
	s_bfe_u32 s55, s64, 0x30003
	s_or_b32 s77, s54, s55
	s_ashr_i32 s58, s64, 6
	s_lshl_b32 s54, s77, 19
	s_mov_b64 s[36:37], s[56:57]
	s_add_u32 s56, s52, s54
	s_addc_u32 s57, s53, 0
	s_ashr_i32 s59, s58, 31
	s_lshl_b64 s[54:55], s[58:59], 19
	s_add_u32 s54, s4, s54
	s_addc_u32 s55, s5, s55
	s_cmpk_lt_i32 s64, 0x580
	s_cselect_b32 s59, s57, s37
	s_cselect_b32 s78, s56, s36
	s_cselect_b32 s79, s55, s63
	s_cselect_b32 s80, s54, s62
	s_add_u32 s81, s62, 0x100
	s_addc_u32 s82, s63, 0
	s_mov_b32 s83, -2
	s_add_u32 s62, s36, 0x100
	s_addc_u32 s63, s37, 0
	s_add_i32 s84, 0, 0x10000
	v_add_u32_e32 v70, s84, v170
	ds_read_b128 v[58:61], v70
	ds_read_b128 v[62:65], v70 offset:1024
	ds_read_b128 v[66:69], v70 offset:2048
	ds_read_b128 v[70:73], v70 offset:3072
	s_cmp_eq_u32 s83, 12
	s_cselect_b32 s67, s59, s63
	s_cselect_b32 s66, s78, s62
	s_cselect_b32 s65, s79, s82
	s_cselect_b32 s64, s80, s81
	v_lshl_add_u64 v[192:193], s[36:37], 0, v[168:169]
	s_add_i32 m0, s69, 0xc000
	ds_read_b128 v[78:81], v175
	ds_read_b128 v[86:89], v175 offset:1024
	ds_read_b128 v[90:93], v175 offset:2048
	ds_read_b128 v[94:97], v175 offset:3072
	ds_read_b128 v[176:179], v175 offset:4096
	ds_read_b128 v[180:183], v175 offset:5120
	ds_read_b128 v[184:187], v175 offset:6144
	ds_read_b128 v[188:191], v175 offset:7168
	global_load_lds_dwordx4 v[192:193], off
	v_lshl_add_u64 v[192:193], s[36:37], 0, v[166:167]
	s_add_i32 m0, s69, 0xe000
	s_nop 0
	global_load_lds_dwordx4 v[192:193], off
	s_waitcnt lgkmcnt(8)
	s_barrier
	s_waitcnt lgkmcnt(0)
	s_waitcnt lgkmcnt(0)
	v_mfma_f32_16x16x32_bf16 v[158:161], v[58:61], v[78:81], 0
	v_mfma_f32_16x16x32_bf16 v[150:153], v[66:69], v[78:81], 0
	v_mfma_f32_16x16x32_bf16 v[142:145], v[58:61], v[90:93], 0
	v_mfma_f32_16x16x32_bf16 v[134:137], v[66:69], v[90:93], 0
	v_mfma_f32_16x16x32_bf16 v[126:129], v[58:61], v[176:179], 0
	v_mfma_f32_16x16x32_bf16 v[118:121], v[66:69], v[176:179], 0
	v_mfma_f32_16x16x32_bf16 v[110:113], v[58:61], v[184:187], 0
	v_mfma_f32_16x16x32_bf16 v[102:105], v[66:69], v[184:187], 0
	v_mfma_f32_16x16x32_bf16 v[158:161], v[62:65], v[86:89], v[158:161]
	v_mfma_f32_16x16x32_bf16 v[150:153], v[70:73], v[86:89], v[150:153]
	v_mfma_f32_16x16x32_bf16 v[142:145], v[62:65], v[94:97], v[142:145]
	v_mfma_f32_16x16x32_bf16 v[134:137], v[70:73], v[94:97], v[134:137]
	v_mfma_f32_16x16x32_bf16 v[126:129], v[62:65], v[180:183], v[126:129]
	v_mfma_f32_16x16x32_bf16 v[118:121], v[70:73], v[180:183], v[118:121]
	v_mfma_f32_16x16x32_bf16 v[110:113], v[62:65], v[188:191], v[110:113]
	v_mfma_f32_16x16x32_bf16 v[102:105], v[70:73], v[188:191], v[102:105]
	s_barrier
	v_mbcnt_lo_u32_b32 v250, -1, 0
	v_mbcnt_hi_u32_b32 v250, -1, v250
	v_lshlrev_b32_e32 v250, 4, v250
	s_lshl_b32 s32, s27, 10
	s_add_u32 s90, s46, s32
	s_addc_u32 s91, s47, 0
	s_add_u32 s92, s48, s32
	s_addc_u32 s93, s49, 0
	s_mov_b32 m0, 0x20840
	s_nop 0
	global_load_lds_dwordx4 v250, s[90:91]
	s_mov_b32 m0, 0x20c40
	s_nop 0
	global_load_lds_dwordx4 v250, s[92:93]
	s_add_i32 s85, 0, 0x14000
	v_add_u32_e32 v192, s85, v170
	s_add_i32 s36, s84, s68
	ds_read_b128 v[200:203], v192
	ds_read_b128 v[204:207], v192 offset:1024
	ds_read_b128 v[208:211], v192 offset:2048
	ds_read_b128 v[222:225], v192 offset:3072
	v_lshl_add_u64 v[192:193], s[64:65], 0, v[164:165]
	s_mov_b32 m0, s36
	v_lshl_add_u64 v[214:215], s[64:65], 0, v[162:163]
	global_load_lds_dwordx4 v[192:193], off
	s_add_i32 m0, s36, 0x2000
	s_nop 0
	global_load_lds_dwordx4 v[214:215], off
	s_barrier
	s_waitcnt lgkmcnt(0)
	s_waitcnt lgkmcnt(0)
	v_mfma_f32_16x16x32_bf16 v[154:157], v[200:203], v[78:81], 0
	v_mfma_f32_16x16x32_bf16 v[78:81], v[208:211], v[78:81], 0
	v_mfma_f32_16x16x32_bf16 v[154:157], v[204:207], v[86:89], v[154:157]
	v_mfma_f32_16x16x32_bf16 v[78:81], v[222:225], v[86:89], v[78:81]
	v_mfma_f32_16x16x32_bf16 v[86:89], v[200:203], v[90:93], 0
	v_mfma_f32_16x16x32_bf16 v[90:93], v[208:211], v[90:93], 0
	v_mfma_f32_16x16x32_bf16 v[114:117], v[208:211], v[176:179], 0
	v_mfma_f32_16x16x32_bf16 v[106:109], v[200:203], v[184:187], 0
	v_mfma_f32_16x16x32_bf16 v[98:101], v[208:211], v[184:187], 0
	v_mfma_f32_16x16x32_bf16 v[86:89], v[204:207], v[94:97], v[86:89]
	v_mfma_f32_16x16x32_bf16 v[90:93], v[222:225], v[94:97], v[90:93]
	v_mfma_f32_16x16x32_bf16 v[94:97], v[200:203], v[176:179], 0
	v_mfma_f32_16x16x32_bf16 v[114:117], v[222:225], v[180:183], v[114:117]
	v_mfma_f32_16x16x32_bf16 v[106:109], v[204:207], v[188:191], v[106:109]
	v_mfma_f32_16x16x32_bf16 v[98:101], v[222:225], v[188:191], v[98:101]
	v_mfma_f32_16x16x32_bf16 v[94:97], v[204:207], v[180:183], v[94:97]
	s_mov_b32 m0, s69
	v_lshl_add_u64 v[234:235], s[66:67], 0, v[164:165]
	s_barrier
	ds_read_b128 v[122:125], v175 offset:16384
	ds_read_b128 v[130:133], v175 offset:17408
	ds_read_b128 v[138:141], v175 offset:18432
	ds_read_b128 v[146:149], v175 offset:19456
	ds_read_b128 v[176:179], v175 offset:20480
	ds_read_b128 v[180:183], v175 offset:21504
	ds_read_b128 v[184:187], v175 offset:22528
	ds_read_b128 v[188:191], v175 offset:23552
	global_load_lds_dwordx4 v[234:235], off
	v_lshl_add_u64 v[236:237], s[66:67], 0, v[162:163]
	s_mov_b32 m0, s70
	s_nop 0
	global_load_lds_dwordx4 v[236:237], off
	s_barrier
	s_waitcnt lgkmcnt(0)
	s_waitcnt lgkmcnt(0)
	v_mfma_f32_16x16x32_bf16 v[82:85], v[58:61], v[122:125], 0
	v_mfma_f32_16x16x32_bf16 v[54:57], v[66:69], v[122:125], 0
	v_mfma_f32_16x16x32_bf16 v[46:49], v[58:61], v[138:141], 0
	v_mfma_f32_16x16x32_bf16 v[38:41], v[66:69], v[138:141], 0
	v_mfma_f32_16x16x32_bf16 v[30:33], v[58:61], v[176:179], 0
	v_mfma_f32_16x16x32_bf16 v[22:25], v[66:69], v[176:179], 0
	v_mfma_f32_16x16x32_bf16 v[14:17], v[58:61], v[184:187], 0
	v_mfma_f32_16x16x32_bf16 v[6:9], v[66:69], v[184:187], 0
	v_mfma_f32_16x16x32_bf16 v[82:85], v[62:65], v[130:133], v[82:85]
	v_mfma_f32_16x16x32_bf16 v[54:57], v[70:73], v[130:133], v[54:57]
	v_mfma_f32_16x16x32_bf16 v[46:49], v[62:65], v[146:149], v[46:49]
	v_mfma_f32_16x16x32_bf16 v[38:41], v[70:73], v[146:149], v[38:41]
	v_mfma_f32_16x16x32_bf16 v[30:33], v[62:65], v[180:183], v[30:33]
	v_mfma_f32_16x16x32_bf16 v[22:25], v[70:73], v[180:183], v[22:25]
	v_mfma_f32_16x16x32_bf16 v[14:17], v[62:65], v[188:191], v[14:17]
	v_mfma_f32_16x16x32_bf16 v[6:9], v[70:73], v[188:191], v[6:9]
	s_barrier
	s_add_u32 s36, s64, 0x40000
	s_addc_u32 s37, s65, 0
	s_add_i32 s84, s85, s68
	v_lshl_add_u64 v[58:59], s[36:37], 0, v[164:165]
	s_mov_b32 m0, s84
	s_nop 0
	global_load_lds_dwordx4 v[58:59], off
	v_lshl_add_u64 v[58:59], s[36:37], 0, v[162:163]
	s_add_i32 m0, s84, 0x2000
	s_nop 0
	global_load_lds_dwordx4 v[58:59], off
	s_waitcnt vmcnt(6)
	s_barrier
	v_mfma_f32_16x16x32_bf16 v[50:53], v[208:211], v[122:125], 0
	v_mfma_f32_16x16x32_bf16 v[42:45], v[200:203], v[138:141], 0
	v_mfma_f32_16x16x32_bf16 v[34:37], v[208:211], v[138:141], 0
	v_mfma_f32_16x16x32_bf16 v[26:29], v[200:203], v[176:179], 0
	v_mfma_f32_16x16x32_bf16 v[18:21], v[208:211], v[176:179], 0
	v_mfma_f32_16x16x32_bf16 v[10:13], v[200:203], v[184:187], 0
	v_mfma_f32_16x16x32_bf16 v[2:5], v[208:211], v[184:187], 0
	v_mfma_f32_16x16x32_bf16 v[58:61], v[200:203], v[122:125], 0
	v_mfma_f32_16x16x32_bf16 v[50:53], v[222:225], v[130:133], v[50:53]
	v_mfma_f32_16x16x32_bf16 v[42:45], v[204:207], v[146:149], v[42:45]
	v_mfma_f32_16x16x32_bf16 v[34:37], v[222:225], v[146:149], v[34:37]
	v_mfma_f32_16x16x32_bf16 v[26:29], v[204:207], v[180:183], v[26:29]
	v_mfma_f32_16x16x32_bf16 v[18:21], v[222:225], v[180:183], v[18:21]
	v_mfma_f32_16x16x32_bf16 v[10:13], v[204:207], v[188:191], v[10:13]
	v_mfma_f32_16x16x32_bf16 v[2:5], v[222:225], v[188:191], v[2:5]
	v_mfma_f32_16x16x32_bf16 v[58:61], v[204:207], v[130:133], v[58:61]
	s_add_i32 s84, 0, 0x18000
	v_add_u32_e32 v74, s84, v170
	s_barrier
	ds_read_b128 v[62:65], v74
	ds_read_b128 v[66:69], v74 offset:1024
	ds_read_b128 v[70:73], v74 offset:2048
	ds_read_b128 v[74:77], v74 offset:3072
	s_add_u32 s36, s66, 0x40000
	s_addc_u32 s37, s67, 0
	s_mov_b32 m0, s71
	v_lshl_add_u64 v[138:139], s[36:37], 0, v[164:165]
	ds_read_b128 v[122:125], v175 offset:32768
	ds_read_b128 v[130:133], v175 offset:33792
	ds_read_b128 v[176:179], v175 offset:34816
	ds_read_b128 v[180:183], v175 offset:35840
	ds_read_b128 v[184:187], v175 offset:36864
	ds_read_b128 v[188:191], v175 offset:37888
	ds_read_b128 v[200:203], v175 offset:38912
	ds_read_b128 v[204:207], v175 offset:39936
	global_load_lds_dwordx4 v[138:139], off
	v_lshl_add_u64 v[138:139], s[36:37], 0, v[162:163]
	s_mov_b32 m0, s72
	s_nop 0
	global_load_lds_dwordx4 v[138:139], off
	s_waitcnt lgkmcnt(8)
	s_barrier
	s_waitcnt lgkmcnt(0)
	s_waitcnt lgkmcnt(0)
	v_mfma_f32_16x16x32_bf16 v[138:141], v[62:65], v[122:125], v[158:161]
	v_mfma_f32_16x16x32_bf16 v[158:161], v[66:69], v[130:133], v[138:141]
	v_mfma_f32_16x16x32_bf16 v[138:141], v[70:73], v[122:125], v[150:153]
	v_mfma_f32_16x16x32_bf16 v[150:153], v[74:77], v[130:133], v[138:141]
	v_mfma_f32_16x16x32_bf16 v[138:141], v[62:65], v[176:179], v[142:145]
	v_mfma_f32_16x16x32_bf16 v[134:137], v[70:73], v[176:179], v[134:137]
	v_mfma_f32_16x16x32_bf16 v[126:129], v[62:65], v[184:187], v[126:129]
	v_mfma_f32_16x16x32_bf16 v[118:121], v[70:73], v[184:187], v[118:121]
	v_mfma_f32_16x16x32_bf16 v[110:113], v[62:65], v[200:203], v[110:113]
	v_mfma_f32_16x16x32_bf16 v[102:105], v[70:73], v[200:203], v[102:105]
	v_mfma_f32_16x16x32_bf16 v[142:145], v[66:69], v[180:183], v[138:141]
	v_mfma_f32_16x16x32_bf16 v[134:137], v[74:77], v[180:183], v[134:137]
	v_mfma_f32_16x16x32_bf16 v[126:129], v[66:69], v[188:191], v[126:129]
	v_mfma_f32_16x16x32_bf16 v[118:121], v[74:77], v[188:191], v[118:121]
	v_mfma_f32_16x16x32_bf16 v[110:113], v[66:69], v[204:207], v[110:113]
	v_mfma_f32_16x16x32_bf16 v[102:105], v[74:77], v[204:207], v[102:105]
	s_barrier
	s_add_i32 s66, 0, 0x1c000
	v_add_u32_e32 v138, s66, v170
	s_add_i32 s36, s84, s68
	ds_read_b128 v[208:211], v138
	ds_read_b128 v[222:225], v138 offset:1024
	ds_read_b128 v[226:229], v138 offset:2048
	ds_read_b128 v[230:233], v138 offset:3072
	v_lshl_add_u64 v[138:139], v[192:193], 0, s[22:23]
	s_mov_b32 m0, s36
	s_nop 0
	global_load_lds_dwordx4 v[138:139], off
	v_lshl_add_u64 v[138:139], v[214:215], 0, s[22:23]
	s_add_i32 m0, s36, 0x2000
	s_nop 0
	global_load_lds_dwordx4 v[138:139], off
	s_barrier
	s_waitcnt lgkmcnt(0)
	s_waitcnt lgkmcnt(0)
	v_mfma_f32_16x16x32_bf16 v[78:81], v[226:229], v[122:125], v[78:81]
	v_mfma_f32_16x16x32_bf16 v[138:141], v[208:211], v[122:125], v[154:157]
	v_mfma_f32_16x16x32_bf16 v[146:149], v[230:233], v[130:133], v[78:81]
	v_mfma_f32_16x16x32_bf16 v[78:81], v[208:211], v[176:179], v[86:89]
	v_mfma_f32_16x16x32_bf16 v[154:157], v[222:225], v[130:133], v[138:141]
	v_mfma_f32_16x16x32_bf16 v[138:141], v[222:225], v[180:183], v[78:81]
	v_mfma_f32_16x16x32_bf16 v[78:81], v[226:229], v[176:179], v[90:93]
	v_mfma_f32_16x16x32_bf16 v[130:133], v[230:233], v[180:183], v[78:81]
	v_mfma_f32_16x16x32_bf16 v[78:81], v[208:211], v[184:187], v[94:97]
	v_mfma_f32_16x16x32_bf16 v[122:125], v[222:225], v[188:191], v[78:81]
	v_mfma_f32_16x16x32_bf16 v[78:81], v[226:229], v[184:187], v[114:117]
	v_mfma_f32_16x16x32_bf16 v[114:117], v[230:233], v[188:191], v[78:81]
	v_mfma_f32_16x16x32_bf16 v[78:81], v[208:211], v[200:203], v[106:109]
	v_mfma_f32_16x16x32_bf16 v[106:109], v[222:225], v[204:207], v[78:81]
	v_mfma_f32_16x16x32_bf16 v[78:81], v[226:229], v[200:203], v[98:101]
	v_mfma_f32_16x16x32_bf16 v[98:101], v[230:233], v[204:207], v[78:81]
	s_mov_b32 m0, s73
	v_lshl_add_u64 v[192:193], v[234:235], 0, s[22:23]
	s_barrier
	s_nop 2
	ds_read_b128 v[78:81], v175 offset:49152
	ds_read_b128 v[86:89], v175 offset:50176
	ds_read_b128 v[90:93], v175 offset:51200
	ds_read_b128 v[94:97], v175 offset:52224
	ds_read_b128 v[176:179], v175 offset:53248
	ds_read_b128 v[180:183], v175 offset:54272
	ds_read_b128 v[184:187], v175 offset:55296
	ds_read_b128 v[188:191], v175 offset:56320
	global_load_lds_dwordx4 v[192:193], off
	v_lshl_add_u64 v[192:193], v[236:237], 0, s[22:23]
	s_mov_b32 m0, s75
	s_nop 0
	global_load_lds_dwordx4 v[192:193], off
	s_barrier
	s_waitcnt lgkmcnt(0)
	s_waitcnt lgkmcnt(0)
	v_mfma_f32_16x16x32_bf16 v[82:85], v[62:65], v[78:81], v[82:85]
	v_mfma_f32_16x16x32_bf16 v[54:57], v[70:73], v[78:81], v[54:57]
	v_mfma_f32_16x16x32_bf16 v[46:49], v[62:65], v[90:93], v[46:49]
	v_mfma_f32_16x16x32_bf16 v[38:41], v[70:73], v[90:93], v[38:41]
	v_mfma_f32_16x16x32_bf16 v[30:33], v[62:65], v[176:179], v[30:33]
	v_mfma_f32_16x16x32_bf16 v[22:25], v[70:73], v[176:179], v[22:25]
	v_mfma_f32_16x16x32_bf16 v[14:17], v[62:65], v[184:187], v[14:17]
	v_mfma_f32_16x16x32_bf16 v[6:9], v[70:73], v[184:187], v[6:9]
	v_mfma_f32_16x16x32_bf16 v[82:85], v[66:69], v[86:89], v[82:85]
	v_mfma_f32_16x16x32_bf16 v[54:57], v[74:77], v[86:89], v[54:57]
	v_mfma_f32_16x16x32_bf16 v[46:49], v[66:69], v[94:97], v[46:49]
	v_mfma_f32_16x16x32_bf16 v[38:41], v[74:77], v[94:97], v[38:41]
	v_mfma_f32_16x16x32_bf16 v[30:33], v[66:69], v[180:183], v[30:33]
	v_mfma_f32_16x16x32_bf16 v[22:25], v[74:77], v[180:183], v[22:25]
	v_mfma_f32_16x16x32_bf16 v[14:17], v[66:69], v[188:191], v[14:17]
	v_mfma_f32_16x16x32_bf16 v[6:9], v[74:77], v[188:191], v[6:9]
	s_barrier
	s_add_u32 s36, s64, 0x40080
	s_addc_u32 s37, s65, 0
	s_add_i32 s64, s66, s68
	v_lshl_add_u64 v[62:63], s[36:37], 0, v[164:165]
	s_mov_b32 m0, s64
	s_nop 0
	global_load_lds_dwordx4 v[62:63], off
	v_lshl_add_u64 v[62:63], s[36:37], 0, v[162:163]
	s_add_i32 m0, s64, 0x2000
	s_nop 0
	global_load_lds_dwordx4 v[62:63], off
	s_waitcnt vmcnt(6)
	s_barrier
	v_mfma_f32_16x16x32_bf16 v[58:61], v[208:211], v[78:81], v[58:61]
	v_mfma_f32_16x16x32_bf16 v[50:53], v[226:229], v[78:81], v[50:53]
	v_mfma_f32_16x16x32_bf16 v[42:45], v[208:211], v[90:93], v[42:45]
	v_mfma_f32_16x16x32_bf16 v[34:37], v[226:229], v[90:93], v[34:37]
	v_mfma_f32_16x16x32_bf16 v[26:29], v[208:211], v[176:179], v[26:29]
	v_mfma_f32_16x16x32_bf16 v[18:21], v[226:229], v[176:179], v[18:21]
	v_mfma_f32_16x16x32_bf16 v[10:13], v[208:211], v[184:187], v[10:13]
	v_mfma_f32_16x16x32_bf16 v[2:5], v[226:229], v[184:187], v[2:5]
	v_mfma_f32_16x16x32_bf16 v[74:77], v[222:225], v[86:89], v[58:61]
	v_mfma_f32_16x16x32_bf16 v[50:53], v[230:233], v[86:89], v[50:53]
	v_mfma_f32_16x16x32_bf16 v[42:45], v[222:225], v[94:97], v[42:45]
	v_mfma_f32_16x16x32_bf16 v[34:37], v[230:233], v[94:97], v[34:37]
	v_mfma_f32_16x16x32_bf16 v[26:29], v[222:225], v[180:183], v[26:29]
	v_mfma_f32_16x16x32_bf16 v[18:21], v[230:233], v[180:183], v[18:21]
	v_mfma_f32_16x16x32_bf16 v[10:13], v[222:225], v[188:191], v[10:13]
	v_mfma_f32_16x16x32_bf16 v[2:5], v[230:233], v[188:191], v[2:5]
	s_add_i32 s83, s83, 2
	s_add_u32 s81, s81, 0x100
	s_addc_u32 s82, s82, 0
	s_cmp_gt_u32 s83, 13
	s_mov_b64 s[36:37], s[62:63]
	s_barrier
